# P0 x-conversion loads issued together with counted waits; L2-warming prefetch loop ahead of compute_rowscale (gate/up and in-proj)
# baseline (speedup 1.0000x reference)
.LBB0_77:
	global_load_dwordx4 v[6:9], v[4:5], off offset:-2048
	global_load_dwordx4 v[10:13], v[4:5], off offset:-1024
	global_load_dwordx4 v[14:17], v[4:5], off
	global_load_dwordx4 v[18:21], v[4:5], off offset:1024
	v_lshl_add_u64 v[24:25], s[14:15], 0, v[2:3]
	v_add_co_u32_e32 v22, vcc, s0, v24
	s_nop 1
	v_addc_co_u32_e32 v23, vcc, 0, v25, vcc
	s_waitcnt vmcnt(3)
	v_cvt_pk_bf16_f32 v24, v6, v7
	v_cvt_pk_bf16_f32 v25, v8, v9
	global_store_dwordx2 v[22:23], v[24:25], off
	v_mul_f32_e32 v7, v7, v7
	v_mul_f32_e32 v9, v9, v9
	v_fmac_f32_e32 v7, v6, v6
	v_fmac_f32_e32 v9, v8, v8
	v_add_f32_e32 v6, v7, v9
	s_waitcnt vmcnt(3)
	v_cvt_pk_bf16_f32 v26, v10, v11
	v_cvt_pk_bf16_f32 v27, v12, v13
	global_store_dwordx2 v[22:23], v[26:27], off offset:512
	v_mul_f32_e32 v7, v11, v11
	v_mul_f32_e32 v8, v13, v13
	v_fmac_f32_e32 v7, v10, v10
	v_fmac_f32_e32 v8, v12, v12
	v_add_f32_e32 v7, v7, v8
	v_add_f32_e32 v6, v6, v7
	s_waitcnt vmcnt(3)
	v_cvt_pk_bf16_f32 v28, v14, v15
	v_cvt_pk_bf16_f32 v29, v16, v17
	global_store_dwordx2 v[22:23], v[28:29], off offset:1024
	v_mul_f32_e32 v7, v15, v15
	v_mul_f32_e32 v8, v17, v17
	v_fmac_f32_e32 v7, v14, v14
	v_fmac_f32_e32 v8, v16, v16
	v_add_f32_e32 v7, v7, v8
	v_add_f32_e32 v6, v6, v7
	s_waitcnt vmcnt(3)
	v_mul_f32_e32 v7, v19, v19
	v_mul_f32_e32 v8, v21, v21
	v_fmac_f32_e32 v7, v18, v18
	v_fmac_f32_e32 v8, v20, v20
	v_add_f32_e32 v7, v7, v8
	v_add_f32_e32 v6, v6, v7
	ds_swizzle_b32 v7, v6 offset:swizzle(SWAP,1)
	s_waitcnt lgkmcnt(0)
	v_add_f32_e32 v6, v6, v7
	ds_swizzle_b32 v7, v6 offset:swizzle(SWAP,2)
	s_waitcnt lgkmcnt(0)
	v_add_f32_e32 v6, v6, v7
	ds_swizzle_b32 v7, v6 offset:swizzle(SWAP,4)
	s_waitcnt lgkmcnt(0)
	v_add_f32_e32 v6, v6, v7
	ds_swizzle_b32 v7, v6 offset:swizzle(SWAP,8)
	s_waitcnt lgkmcnt(0)
	v_add_f32_e32 v8, v6, v7
	ds_swizzle_b32 v9, v8 offset:swizzle(SWAP,16)
	v_cvt_pk_bf16_f32 v6, v18, v19
	v_cvt_pk_bf16_f32 v7, v20, v21
	global_store_dwordx2 v[22:23], v[6:7], off offset:1536
	s_waitcnt lgkmcnt(0)
	v_add_f32_e32 v6, v8, v9
	v_mov_b32_e32 v7, v6
	s_nop 1
	v_permlane32_swap_b32_e32 v6, v7
	s_and_saveexec_b64 s[22:23], s[6:7]
	s_cbranch_execz .LBB0_76
	v_add_f32_e32 v6, v6, v7
	v_lshl_add_u64 v[8:9], s[14:15], 0, v[0:1]
	v_cndmask_b32_e64 v6, 0, v6, s[4:5]
	global_store_dword v[8:9], v6, off
	s_branch .LBB0_76

.LBB0_596:
	s_or_b64 exec, exec, s[4:5]
	s_mov_b32 s45, s72
	s_mov_b32 s16, s71
	v_mbcnt_lo_u32_b32 v0, -1, 0
	v_mbcnt_hi_u32_b32 v0, -1, v0
	s_getreg_b32 s2, hwreg(HW_REG_HW_ID, 0, 6)
	s_lshl_b32 s2, s2, 2
	s_and_b32 s2, s2, 0xfc
	s_add_i32 s2, s2, 0
	s_add_i32 s2, s2, 0x23400
	v_mov_b32_e32 v2, s2
	ds_read_b32 v2, v2
	v_and_b32_e32 v6, 1, v0
	s_ashr_i32 s17, s16, 31
	s_ashr_i32 s46, s45, 31
	v_cmp_eq_u32_e64 s[4:5], 0, v6
	s_waitcnt lgkmcnt(0)
	v_readfirstlane_b32 s2, v2
	s_mov_b64 s[6:7], s[16:17]
	s_nop 0
	v_lshl_add_u32 v2, s2, 6, v0
	v_ashrrev_i32_e32 v4, 1, v2
	v_ashrrev_i32_e32 v5, 31, v4
	v_lshlrev_b64 v[2:3], 7, v[4:5]
	v_lshl_add_u64 v[2:3], s[12:13], 0, v[2:3]
	v_lshlrev_b32_e32 v0, 6, v6
	v_lshl_add_u64 v[2:3], v[2:3], 0, v[0:1]
	s_mov_b64 s[2:3], 0x100000
	v_lshl_add_u64 v[2:3], v[2:3], 0, s[2:3]
	v_readlane_b32 s2, v255, 4
	s_nop 1
	v_lshl_add_u32 v0, v4, 2, s2
	s_mov_b32 s100, s6
.Lrs_pf_loop2:
	s_ashr_i32 s2, s100, 31
	s_lshr_b32 s2, s2, 29
	s_add_i32 s2, s100, s2
	s_ashr_i32 s3, s2, 3
	s_and_b32 s2, s2, -8
	s_sub_i32 s2, s100, s2
	s_cmp_lt_i32 s2, 0
	s_cselect_b32 s8, s77, 0xd0
	s_mul_i32 s2, s2, s8
	s_add_i32 s2, s2, s3
	s_mul_hi_i32 s3, s2, 0x4ec4ec4f
	s_lshr_b32 s8, s3, 31
	s_ashr_i32 s3, s3, 5
	s_add_i32 s3, s3, s8
	s_lshl_b32 s8, s3, 3
	s_sub_i32 s9, 0x80, s8
	s_min_i32 s9, s9, 8
	s_abs_i32 s9, s9
	v_cvt_f32_u32_e32 v4, s9
	s_sub_i32 s10, 0, s9
	s_mulk_i32 s3, 0x68
	s_sub_i32 s2, s2, s3
	v_rcp_iflag_f32_e32 v4, v4
	s_ashr_i32 s3, s2, 31
	s_abs_i32 s2, s2
	v_mul_f32_e32 v4, 0x4f7ffffe, v4
	v_cvt_u32_f32_e32 v4, v4
	s_nop 0
	v_readfirstlane_b32 s11, v4
	s_mul_i32 s10, s10, s11
	s_mul_hi_u32 s10, s11, s10
	s_add_i32 s11, s11, s10
	s_mul_hi_u32 s10, s2, s11
	s_mul_i32 s10, s10, s9
	s_sub_i32 s2, s2, s10
	s_sub_i32 s10, s2, s9
	s_cmp_ge_u32 s2, s9
	s_cselect_b32 s2, s10, s2
	s_sub_i32 s10, s2, s9
	s_cmp_ge_u32 s2, s9
	s_cselect_b32 s2, s10, s2
	s_xor_b32 s2, s2, s3
	s_sub_i32 s2, s2, s3
	s_add_i32 s2, s8, s2
	s_ashr_i32 s3, s2, 31
	s_lshl_b64 s[2:3], s[2:3], 15
	v_lshl_add_u64 v[16:17], v[2:3], 0, s[2:3]
	global_load_dword v20, v[16:17], off
	s_add_i32 s100, s100, s45
	s_cmp_lt_u32 s100, 0x680
	s_cbranch_scc1 .Lrs_pf_loop2
	s_branch .LBB0_599

.LBB0_1081:
.LBB0_1082:
	s_mov_b64 s[2:3], s[84:85]
	s_mov_b32 s34, s72
	s_mov_b32 s6, s71
	s_load_dwordx2 s[12:13], s[2:3], 0x110
	v_mbcnt_lo_u32_b32 v0, -1, 0
	v_mbcnt_hi_u32_b32 v0, -1, v0
	s_getreg_b32 s2, hwreg(HW_REG_HW_ID, 0, 6)
	s_lshl_b32 s2, s2, 2
	s_and_b32 s2, s2, 0xfc
	s_add_i32 s2, s2, 0
	s_add_i32 s2, s2, 0x23400
	v_mov_b32_e32 v2, s2
	ds_read_b32 v2, v2
	v_and_b32_e32 v6, 1, v0
	s_ashr_i32 s7, s6, 31
	s_xor_b64 s[10:11], s[58:59], -1
	s_ashr_i32 s35, s34, 31
	s_waitcnt lgkmcnt(0)
	v_readfirstlane_b32 s2, v2
	v_cmp_eq_u32_e64 s[4:5], 0, v6
	s_mov_b64 s[8:9], s[6:7]
	v_lshl_add_u32 v2, s2, 6, v0
	v_ashrrev_i32_e32 v4, 1, v2
	v_ashrrev_i32_e32 v5, 31, v4
	v_lshlrev_b64 v[2:3], 7, v[4:5]
	v_lshl_add_u64 v[2:3], s[12:13], 0, v[2:3]
	v_lshlrev_b32_e32 v0, 6, v6
	v_lshl_add_u64 v[2:3], v[2:3], 0, v[0:1]
	s_mov_b64 s[2:3], 0x100000
	v_lshl_add_u64 v[2:3], v[2:3], 0, s[2:3]
	v_readlane_b32 s2, v255, 4
	s_nop 1
	v_lshl_add_u32 v0, v4, 2, s2
	s_mov_b32 s100, s8
.Lrs_pf_loop:
	s_ashr_i32 s2, s100, 31
	s_lshr_b32 s2, s2, 29
	s_add_i32 s2, s100, s2
	s_ashr_i32 s3, s2, 3
	s_and_b32 s2, s2, -8
	s_sub_i32 s2, s100, s2
	s_cmp_lt_i32 s2, 0
	s_cselect_b32 s14, s62, 0x160
	s_mul_i32 s2, s2, s14
	s_add_i32 s2, s2, s3
	s_mul_hi_i32 s3, s2, 0x2e8ba2e9
	s_lshr_b32 s14, s3, 31
	s_ashr_i32 s3, s3, 5
	s_add_i32 s3, s3, s14
	s_lshl_b32 s14, s3, 3
	s_sub_i32 s15, 0x80, s14
	s_min_i32 s15, s15, 8
	s_abs_i32 s15, s15
	v_cvt_f32_u32_e32 v4, s15
	s_sub_i32 s16, 0, s15
	s_mulk_i32 s3, 0xb0
	s_sub_i32 s2, s2, s3
	v_rcp_iflag_f32_e32 v4, v4
	s_ashr_i32 s3, s2, 31
	s_abs_i32 s2, s2
	v_mul_f32_e32 v4, 0x4f7ffffe, v4
	v_cvt_u32_f32_e32 v4, v4
	s_nop 0
	v_readfirstlane_b32 s17, v4
	s_mul_i32 s16, s16, s17
	s_mul_hi_u32 s16, s17, s16
	s_add_i32 s17, s17, s16
	s_mul_hi_u32 s16, s2, s17
	s_mul_i32 s16, s16, s15
	s_sub_i32 s2, s2, s16
	s_sub_i32 s16, s2, s15
	s_cmp_ge_u32 s2, s15
	s_cselect_b32 s2, s16, s2
	s_sub_i32 s16, s2, s15
	s_cmp_ge_u32 s2, s15
	s_cselect_b32 s2, s16, s2
	s_xor_b32 s2, s2, s3
	s_sub_i32 s2, s2, s3
	s_add_i32 s2, s14, s2
	s_ashr_i32 s3, s2, 31
	s_lshl_b64 s[2:3], s[2:3], 15
	v_lshl_add_u64 v[16:17], v[2:3], 0, s[2:3]
	global_load_dword v20, v[16:17], off
	s_add_i32 s100, s100, s34
	s_cmp_lt_u32 s100, 0xb00
	s_cbranch_scc1 .Lrs_pf_loop
	s_branch .LBB0_1085
